# variant WITHOUT the rcp-based divisions (IEEE division sequences kept): all other edits of combo8
# baseline (speedup 1.0000x reference)
; DI float bf2f(u16 v) { return __uint_as_float((unsigned)v << 16); }
; DI float lo16(unsigned w) { return __uint_as_float(w << 16); }
; DI float hi16(unsigned w) { return __uint_as_float(w & 0xffff0000u); }
; DI float sigmoidf_(float x) { return 1.f / (1.f + __expf(-x)); }
; DI float siluf_(float x) { return x / (1.f + __expf(-x)); }
; DI void nsa_item(const Params& p, int it, char* lds) {
;     ...
;   const float g0 = sigmoidf_(bf2f(proj[tok * NP + C_AG + 0 + h])), g1 = sigmoidf_(bf2f(proj[tok * NP + C_AG + 4 + h])), g2 = sigmoidf_(bf2f(proj[tok * NP + C_AG + 8 + h]));
;     ...
;   lsum += __shfl_xor(lsum, 32, 64);
;   const float il = g1 / lsum;
;   const u16* ow = (const u16*)(ws_ + OFF_OWIN);
;   u16* y = (u16*)(ws_ + OFF_XB);
; #pragma unroll
;   for (int db = 0; db < 2; ++db)
; #pragma unroll
;     for (int g = 0; g < 4; ++g) {
;       const int col = h * 64 + 32 * db + 8 * g + 4 * hi;
;       const u32x2 w = *(const u32x2*)(ow + tok * 256 + col), az = *(const u32x2*)(proj + tok * NP + C_AZ + col);
;       const float v0 = (ya[db][4 * g] + o[db][4 * g] * il + g2 * lo16(w[0])) * siluf_(lo16(az[0]));
;       const float v1 = (ya[db][4 * g + 1] + o[db][4 * g + 1] * il + g2 * hi16(w[0])) * siluf_(hi16(az[0]));
;       const float v2 = (ya[db][4 * g + 2] + o[db][4 * g + 2] * il + g2 * lo16(w[1])) * siluf_(lo16(az[1]));
;       const float v3 = (ya[db][4 * g + 3] + o[db][4 * g + 3] * il + g2 * hi16(w[1])) * siluf_(hi16(az[1]));
.LBB0_405:
	v_lshlrev_b32_e32 v32, 16, v155
	v_mul_f32_e32 v32, 0xbfb8aa3b, v32
	v_exp_f32_e32 v32, v32
	ds_bpermute_b32 v181, v158, v151
	v_mov_b32_e32 v147, v179
	v_lshlrev_b64 v[72:73], 11, v[146:147]
	v_add_f32_e32 v32, 1.0, v32
	v_div_scale_f32 v33, s[0:1], v32, v32, 1.0
	v_rcp_f32_e32 v34, v33
	v_readlane_b32 s13, v234, 36
	v_readlane_b32 s12, v234, 33
	v_readlane_b32 s14, v234, 37
	v_fma_f32 v35, -v33, v34, 1.0
	v_fmac_f32_e32 v34, v35, v34
	v_div_scale_f32 v35, vcc, 1.0, v32, 1.0
	v_mul_f32_e32 v36, v35, v34
	v_fma_f32 v37, -v33, v36, v35
	v_fmac_f32_e32 v36, v37, v34
	v_fma_f32 v33, -v33, v36, v35
	v_div_fmas_f32 v33, v33, v34, v36
	v_div_fixup_f32 v32, v33, v32, 1.0
	v_lshlrev_b32_e32 v33, 16, v154
	v_mul_f32_e32 v33, 0xbfb8aa3b, v33
	v_exp_f32_e32 v150, v33
	ds_read2st64_b32 v[70:71], v161 offset0:144 offset1:148
	ds_read2st64_b32 v[54:55], v161 offset0:208 offset1:212
	ds_read2st64_b32 v[68:69], v161 offset0:152 offset1:156
	ds_read2st64_b32 v[52:53], v161 offset0:216 offset1:220
	ds_read2st64_b32 v[66:67], v161 offset0:160 offset1:164
	ds_read2st64_b32 v[50:51], v161 offset0:224 offset1:228
	ds_read2st64_b32 v[64:65], v161 offset0:168 offset1:172
	ds_read2st64_b32 v[48:49], v161 offset0:232 offset1:236
	ds_read2st64_b32 v[62:63], v161 offset0:176 offset1:180
	ds_read2st64_b32 v[46:47], v161 offset0:240 offset1:244
	ds_read2st64_b32 v[60:61], v161 offset0:184 offset1:188
	ds_read2st64_b32 v[44:45], v161 offset0:248 offset1:252
	ds_read2st64_b32 v[58:59], v161 offset0:192 offset1:196
	ds_read_b32 v38, v162
	ds_read_b32 v39, v163
	ds_read2st64_b32 v[56:57], v161 offset0:200 offset1:204
	ds_read_b32 v34, v164
	ds_read_b32 v35, v165
	s_waitcnt lgkmcnt(14)
	v_pk_add_f32 v[36:37], v[150:151], v[180:181]
	s_nop 0
	v_div_scale_f32 v33, s[0:1], v36, v36, 1.0
	v_rcp_f32_e32 v40, v33
	s_nop 0
	v_fma_f32 v41, -v33, v40, 1.0
	v_fmac_f32_e32 v40, v41, v40
	v_div_scale_f32 v41, vcc, 1.0, v36, 1.0
	v_mul_f32_e32 v42, v41, v40
	v_fma_f32 v43, -v33, v42, v41
	v_fmac_f32_e32 v42, v43, v40
	v_fma_f32 v33, -v33, v42, v41
	v_div_fmas_f32 v33, v33, v40, v42
	v_div_fixup_f32 v33, v33, v36, 1.0
	v_div_scale_f32 v36, s[0:1], v37, v37, v33
	v_rcp_f32_e32 v40, v36
	v_readlane_b32 s0, v234, 38
	v_readlane_b32 s1, v234, 39
	v_fma_f32 v41, -v36, v40, 1.0
	v_fmac_f32_e32 v40, v41, v40
	v_div_scale_f32 v41, vcc, v33, v37, v33
	v_mul_f32_e32 v42, v41, v40
	v_fma_f32 v43, -v36, v42, v41
	v_fmac_f32_e32 v42, v43, v40
	v_fma_f32 v36, -v36, v42, v41
	v_div_fmas_f32 v36, v36, v40, v42
	v_or_b32_e32 v40, v156, v148
	v_lshlrev_b64 v[42:43], 9, v[146:147]
	v_ashrrev_i32_e32 v41, 31, v40
	v_lshl_add_u64 v[42:43], s[0:1], 0, v[42:43]
	v_lshlrev_b64 v[74:75], 1, v[40:41]
	v_lshl_add_u64 v[72:73], s[0:1], 0, v[72:73]
	v_lshl_add_u64 v[40:41], v[42:43], 0, v[74:75]
	s_mov_b64 s[0:1], 0xb390000
	v_lshl_add_u64 v[42:43], v[40:41], 0, s[0:1]
	s_mov_b32 s0, 0xb390000
	v_add_co_u32_e32 v40, vcc, s0, v40
	v_div_fixup_f32 v36, v36, v37, v33
	s_nop 0
	v_addc_co_u32_e32 v41, vcc, 0, v41, vcc
	global_load_dwordx2 v[76:77], v[40:41], off
	v_lshl_add_u64 v[40:41], v[144:145], 0, v[74:75]
	global_load_dwordx2 v[78:79], v[40:41], off offset:1280
	s_waitcnt vmcnt(0)
	v_and_b32_e32 v37, 0xffff0000, v78
	v_lshlrev_b32_e32 v33, 16, v78
	v_pk_fma_f32 v[16:17], v[16:17], v[36:37], v[70:71] op_sel_hi:[1,0,1]
	v_lshlrev_b32_e32 v70, 16, v76
	v_and_b32_e32 v71, 0xffff0000, v76
	v_mul_f32_e32 v78, 0xbfb8aa3b, v33
	v_pk_fma_f32 v[16:17], v[32:33], v[70:71], v[16:17] op_sel_hi:[0,1,1]
	v_mul_f32_e32 v70, 0xbfb8aa3b, v37
	v_exp_f32_e32 v80, v78
	v_exp_f32_e32 v81, v70
	s_nop 0
	v_pk_add_f32 v[70:71], v[80:81], 1.0 op_sel_hi:[1,0]
	s_nop 0
	v_div_scale_f32 v76, s[0:1], v71, v71, v37
	v_rcp_f32_e32 v78, v76
	s_nop 0
	v_fma_f32 v80, -v76, v78, 1.0
	v_fmac_f32_e32 v78, v80, v78
	v_div_scale_f32 v80, vcc, v37, v71, v37
	v_mul_f32_e32 v81, v80, v78
	v_fma_f32 v82, -v76, v81, v80
	v_fmac_f32_e32 v81, v82, v78
	v_fma_f32 v76, -v76, v81, v80
	v_div_fmas_f32 v76, v76, v78, v81
	v_div_fixup_f32 v71, v76, v71, v37
	v_div_scale_f32 v37, s[0:1], v70, v70, v33
	v_rcp_f32_e32 v76, v37
	s_nop 0
	v_fma_f32 v78, -v37, v76, 1.0
	v_fmac_f32_e32 v76, v78, v76
	v_div_scale_f32 v78, vcc, v33, v70, v33
	v_mul_f32_e32 v80, v78, v76
	v_fma_f32 v81, -v37, v80, v78
	v_fmac_f32_e32 v80, v81, v76
	v_fma_f32 v37, -v37, v80, v78
	v_div_fmas_f32 v37, v37, v76, v80
	v_div_fixup_f32 v70, v37, v70, v33
	v_and_b32_e32 v37, 0xffff0000, v79
	v_lshlrev_b32_e32 v33, 16, v79
	v_pk_fma_f32 v[18:19], v[18:19], v[36:37], v[68:69] op_sel_hi:[1,0,1]
	v_lshlrev_b32_e32 v68, 16, v77
	v_and_b32_e32 v69, 0xffff0000, v77
	v_pk_mul_f32 v[16:17], v[16:17], v[70:71]
	v_mul_f32_e32 v70, 0xbfb8aa3b, v33
	v_pk_fma_f32 v[18:19], v[32:33], v[68:69], v[18:19] op_sel_hi:[0,1,1]
	v_mul_f32_e32 v68, 0xbfb8aa3b, v37
	v_exp_f32_e32 v70, v70
	v_exp_f32_e32 v71, v68
	s_nop 0
	v_pk_add_f32 v[68:69], v[70:71], 1.0 op_sel_hi:[1,0]
	s_nop 0
	v_div_scale_f32 v70, s[0:1], v69, v69, v37
	v_rcp_f32_e32 v71, v70
	s_nop 0
	v_fma_f32 v76, -v70, v71, 1.0
	v_fmac_f32_e32 v71, v76, v71
	v_div_scale_f32 v76, vcc, v37, v69, v37
	v_mul_f32_e32 v77, v76, v71
	v_fma_f32 v78, -v70, v77, v76
	v_fmac_f32_e32 v77, v78, v71
	v_fma_f32 v70, -v70, v77, v76
	v_div_fmas_f32 v70, v70, v71, v77
	v_div_fixup_f32 v69, v70, v69, v37
	v_div_scale_f32 v37, s[0:1], v68, v68, v33
	v_rcp_f32_e32 v70, v37
	s_mov_b64 s[0:1], 0x2a40000
	v_fma_f32 v71, -v37, v70, 1.0
	v_fmac_f32_e32 v70, v71, v70
	v_div_scale_f32 v71, vcc, v33, v68, v33
	v_mul_f32_e32 v76, v71, v70
	v_fma_f32 v77, -v37, v76, v71
	v_fmac_f32_e32 v76, v77, v70
	v_fma_f32 v37, -v37, v76, v71
	v_div_fmas_f32 v37, v37, v70, v76
	v_div_fixup_f32 v68, v37, v68, v33
	v_pk_mul_f32 v[18:19], v[18:19], v[68:69]
	v_cvt_pk_bf16_f32 v68, v16, v17
	v_cvt_pk_bf16_f32 v69, v18, v19
	v_lshl_add_u64 v[18:19], v[72:73], 0, v[74:75]
	v_lshl_add_u64 v[16:17], v[18:19], 0, s[0:1]
	v_add_co_u32_e32 v18, vcc, s74, v18
	s_nop 1
	v_addc_co_u32_e32 v19, vcc, 0, v19, vcc
	global_store_dwordx2 v[18:19], v[68:69], off
	global_load_dwordx2 v[18:19], v[42:43], off offset:16
	s_nop 0
	global_load_dwordx2 v[68:69], v[40:41], off offset:1296
	s_waitcnt vmcnt(0)
; DI float lo16(unsigned w) { return __uint_as_float(w << 16); }
; DI float hi16(unsigned w) { return __uint_as_float(w & 0xffff0000u); }
; DI float siluf_(float x) { return x / (1.f + __expf(-x)); }
; DI void nsa_item(const Params& p, int it, char* lds) {
;     ...
; #pragma unroll
;   for (int db = 0; db < 2; ++db)
; #pragma unroll
;     for (int g = 0; g < 4; ++g) {
;       const int col = h * 64 + 32 * db + 8 * g + 4 * hi;
;       const u32x2 w = *(const u32x2*)(ow + tok * 256 + col), az = *(const u32x2*)(proj + tok * NP + C_AZ + col);
;       const float v0 = (ya[db][4 * g] + o[db][4 * g] * il + g2 * lo16(w[0])) * siluf_(lo16(az[0]));
;       const float v1 = (ya[db][4 * g + 1] + o[db][4 * g + 1] * il + g2 * hi16(w[0])) * siluf_(hi16(az[0]));
;       const float v2 = (ya[db][4 * g + 2] + o[db][4 * g + 2] * il + g2 * lo16(w[1])) * siluf_(lo16(az[1]));
;       const float v3 = (ya[db][4 * g + 3] + o[db][4 * g + 3] * il + g2 * hi16(w[1])) * siluf_(hi16(az[1]));
	v_lshlrev_b32_e32 v33, 16, v68
	v_and_b32_e32 v37, 0xffff0000, v68
	v_mul_f32_e32 v68, 0xbfb8aa3b, v33
	s_waitcnt lgkmcnt(13)
	v_pk_fma_f32 v[20:21], v[20:21], v[36:37], v[66:67] op_sel_hi:[1,0,1]
	v_lshlrev_b32_e32 v66, 16, v18
	v_and_b32_e32 v67, 0xffff0000, v18
	v_mul_f32_e32 v18, 0xbfb8aa3b, v37
	v_exp_f32_e32 v70, v68
	v_exp_f32_e32 v71, v18
	v_pk_fma_f32 v[20:21], v[32:33], v[66:67], v[20:21] op_sel_hi:[0,1,1]
	v_pk_add_f32 v[66:67], v[70:71], 1.0 op_sel_hi:[1,0]
	s_nop 0
	v_div_scale_f32 v18, s[0:1], v67, v67, v37
	v_rcp_f32_e32 v68, v18
	s_nop 0
	v_fma_f32 v70, -v18, v68, 1.0
	v_fmac_f32_e32 v68, v70, v68
	v_div_scale_f32 v70, vcc, v37, v67, v37
	v_mul_f32_e32 v71, v70, v68
	v_fma_f32 v72, -v18, v71, v70
	v_fmac_f32_e32 v71, v72, v68
	v_fma_f32 v18, -v18, v71, v70
	v_div_fmas_f32 v18, v18, v68, v71
	v_div_fixup_f32 v67, v18, v67, v37
	v_div_scale_f32 v18, s[0:1], v66, v66, v33
	v_rcp_f32_e32 v37, v18
	s_nop 0
	v_fma_f32 v68, -v18, v37, 1.0
	v_fmac_f32_e32 v37, v68, v37
	v_div_scale_f32 v68, vcc, v33, v66, v33
	v_mul_f32_e32 v70, v68, v37
	v_fma_f32 v71, -v18, v70, v68
	v_fmac_f32_e32 v70, v71, v37
	v_fma_f32 v18, -v18, v70, v68
	v_div_fmas_f32 v18, v18, v37, v70
	v_div_fixup_f32 v66, v18, v66, v33
	v_lshlrev_b32_e32 v33, 16, v69
	v_and_b32_e32 v37, 0xffff0000, v69
	v_mul_f32_e32 v18, 0xbfb8aa3b, v33
	s_waitcnt lgkmcnt(11)
	v_pk_fma_f32 v[22:23], v[22:23], v[36:37], v[64:65] op_sel_hi:[1,0,1]
	v_lshlrev_b32_e32 v64, 16, v19
	v_and_b32_e32 v65, 0xffff0000, v19
	v_mul_f32_e32 v19, 0xbfb8aa3b, v37
	v_exp_f32_e32 v18, v18
	v_exp_f32_e32 v19, v19
	v_pk_fma_f32 v[22:23], v[32:33], v[64:65], v[22:23] op_sel_hi:[0,1,1]
	v_pk_mul_f32 v[20:21], v[20:21], v[66:67]
	v_pk_add_f32 v[18:19], v[18:19], 1.0 op_sel_hi:[1,0]
	s_nop 0
	v_div_scale_f32 v64, s[0:1], v19, v19, v37
	v_rcp_f32_e32 v65, v64
	v_cvt_pk_bf16_f32 v20, v20, v21
	v_fma_f32 v66, -v64, v65, 1.0
	v_fmac_f32_e32 v65, v66, v65
	v_div_scale_f32 v66, vcc, v37, v19, v37
	v_mul_f32_e32 v67, v66, v65
	v_fma_f32 v68, -v64, v67, v66
	v_fmac_f32_e32 v67, v68, v65
	v_fma_f32 v64, -v64, v67, v66
	v_div_fmas_f32 v64, v64, v65, v67
	v_div_fixup_f32 v19, v64, v19, v37
	v_div_scale_f32 v37, s[0:1], v18, v18, v33
	v_rcp_f32_e32 v64, v37
	s_nop 0
	v_fma_f32 v65, -v37, v64, 1.0
	v_fmac_f32_e32 v64, v65, v64
	v_div_scale_f32 v65, vcc, v33, v18, v33
	v_mul_f32_e32 v66, v65, v64
	v_fma_f32 v67, -v37, v66, v65
	v_fmac_f32_e32 v66, v67, v64
	v_fma_f32 v37, -v37, v66, v65
	v_div_fmas_f32 v37, v37, v64, v66
	v_div_fixup_f32 v18, v37, v18, v33
	v_pk_mul_f32 v[18:19], v[22:23], v[18:19]
	s_waitcnt lgkmcnt(9)
	v_pk_fma_f32 v[24:25], v[24:25], v[36:37], v[62:63] op_sel_hi:[1,0,1]
	v_cvt_pk_bf16_f32 v21, v18, v19
	global_store_dwordx2 v[16:17], v[20:21], off offset:16
	global_load_dwordx2 v[18:19], v[42:43], off offset:32
	s_nop 0
	global_load_dwordx2 v[20:21], v[40:41], off offset:1312
	s_waitcnt vmcnt(1)
	v_lshlrev_b32_e32 v62, 16, v18
	s_waitcnt vmcnt(0)
	v_lshlrev_b32_e32 v33, 16, v20
	v_and_b32_e32 v20, 0xffff0000, v20
	v_mul_f32_e32 v22, 0xbfb8aa3b, v33
	v_and_b32_e32 v63, 0xffff0000, v18
	v_mul_f32_e32 v18, 0xbfb8aa3b, v20
	v_exp_f32_e32 v22, v22
	v_exp_f32_e32 v23, v18
	v_pk_fma_f32 v[24:25], v[32:33], v[62:63], v[24:25] op_sel_hi:[0,1,1]
	v_pk_add_f32 v[22:23], v[22:23], 1.0 op_sel_hi:[1,0]
	s_nop 0
	v_div_scale_f32 v18, s[0:1], v23, v23, v20
	v_rcp_f32_e32 v37, v18
	s_nop 0
	v_fma_f32 v62, -v18, v37, 1.0
	v_fmac_f32_e32 v37, v62, v37
	v_div_scale_f32 v62, vcc, v20, v23, v20
	v_mul_f32_e32 v63, v62, v37
	v_fma_f32 v64, -v18, v63, v62
	v_fmac_f32_e32 v63, v64, v37
	v_fma_f32 v18, -v18, v63, v62
	v_div_fmas_f32 v18, v18, v37, v63
	v_div_fixup_f32 v23, v18, v23, v20
	v_div_scale_f32 v18, s[0:1], v22, v22, v33
	v_rcp_f32_e32 v20, v18
	s_nop 0
	v_fma_f32 v37, -v18, v20, 1.0
	v_fmac_f32_e32 v20, v37, v20
	v_div_scale_f32 v37, vcc, v33, v22, v33
	v_mul_f32_e32 v62, v37, v20
	v_fma_f32 v63, -v18, v62, v37
	v_fmac_f32_e32 v62, v63, v20
	v_fma_f32 v18, -v18, v62, v37
	v_div_fmas_f32 v18, v18, v20, v62
	v_div_fixup_f32 v22, v18, v22, v33
	v_lshlrev_b32_e32 v33, 16, v21
	v_and_b32_e32 v37, 0xffff0000, v21
	v_pk_mul_f32 v[22:23], v[24:25], v[22:23]
	v_mul_f32_e32 v18, 0xbfb8aa3b, v33
	v_lshlrev_b32_e32 v24, 16, v19
	v_and_b32_e32 v25, 0xffff0000, v19
	v_mul_f32_e32 v19, 0xbfb8aa3b, v37
	v_exp_f32_e32 v18, v18
	v_exp_f32_e32 v19, v19
	s_waitcnt lgkmcnt(7)
	v_pk_fma_f32 v[20:21], v[26:27], v[36:37], v[60:61] op_sel_hi:[1,0,1]
	v_pk_add_f32 v[18:19], v[18:19], 1.0 op_sel_hi:[1,0]
	v_pk_fma_f32 v[20:21], v[32:33], v[24:25], v[20:21] op_sel_hi:[0,1,1]
	v_div_scale_f32 v24, s[0:1], v19, v19, v37
	v_rcp_f32_e32 v25, v24
	s_nop 0
	v_fma_f32 v26, -v24, v25, 1.0
	v_fmac_f32_e32 v25, v26, v25
	v_div_scale_f32 v26, vcc, v37, v19, v37
	v_mul_f32_e32 v27, v26, v25
	v_fma_f32 v60, -v24, v27, v26
	v_fmac_f32_e32 v27, v60, v25
	v_fma_f32 v24, -v24, v27, v26
	v_div_fmas_f32 v24, v24, v25, v27
	v_div_fixup_f32 v19, v24, v19, v37
	v_div_scale_f32 v24, s[0:1], v18, v18, v33
	v_rcp_f32_e32 v25, v24
	s_nop 0
	v_fma_f32 v26, -v24, v25, 1.0
	v_fmac_f32_e32 v25, v26, v25
	v_div_scale_f32 v26, vcc, v33, v18, v33
	v_mul_f32_e32 v27, v26, v25
	v_fma_f32 v37, -v24, v27, v26
	v_fmac_f32_e32 v27, v37, v25
	v_fma_f32 v24, -v24, v27, v26
	v_div_fmas_f32 v24, v24, v25, v27
	v_div_fixup_f32 v18, v24, v18, v33
	v_pk_mul_f32 v[18:19], v[20:21], v[18:19]
	v_cvt_pk_bf16_f32 v20, v22, v23
	v_cvt_pk_bf16_f32 v21, v18, v19
	global_store_dwordx2 v[16:17], v[20:21], off offset:32
	global_load_dwordx2 v[18:19], v[42:43], off offset:48
	s_nop 0
	global_load_dwordx2 v[20:21], v[40:41], off offset:1328
	s_waitcnt lgkmcnt(5)
; DI float lo16(unsigned w) { return __uint_as_float(w << 16); }
; DI float hi16(unsigned w) { return __uint_as_float(w & 0xffff0000u); }
; DI float siluf_(float x) { return x / (1.f + __expf(-x)); }
; DI void nsa_item(const Params& p, int it, char* lds) {
;     ...
; #pragma unroll
;   for (int db = 0; db < 2; ++db)
; #pragma unroll
;     for (int g = 0; g < 4; ++g) {
;       const int col = h * 64 + 32 * db + 8 * g + 4 * hi;
;       const u32x2 w = *(const u32x2*)(ow + tok * 256 + col), az = *(const u32x2*)(proj + tok * NP + C_AZ + col);
;       const float v0 = (ya[db][4 * g] + o[db][4 * g] * il + g2 * lo16(w[0])) * siluf_(lo16(az[0]));
;       const float v1 = (ya[db][4 * g + 1] + o[db][4 * g + 1] * il + g2 * hi16(w[0])) * siluf_(hi16(az[0]));
;       const float v2 = (ya[db][4 * g + 2] + o[db][4 * g + 2] * il + g2 * lo16(w[1])) * siluf_(lo16(az[1]));
;       const float v3 = (ya[db][4 * g + 3] + o[db][4 * g + 3] * il + g2 * hi16(w[1])) * siluf_(hi16(az[1]));
	v_pk_fma_f32 v[24:25], v[28:29], v[36:37], v[58:59] op_sel_hi:[1,0,1]
	v_pk_fma_f32 v[0:1], v[0:1], v[36:37], v[54:55] op_sel_hi:[1,0,1]
	v_pk_fma_f32 v[2:3], v[2:3], v[36:37], v[52:53] op_sel_hi:[1,0,1]
	v_pk_fma_f32 v[4:5], v[4:5], v[36:37], v[50:51] op_sel_hi:[1,0,1]
	s_waitcnt vmcnt(1)
	v_lshlrev_b32_e32 v26, 16, v18
	s_waitcnt vmcnt(0)
	v_lshlrev_b32_e32 v33, 16, v20
	v_and_b32_e32 v20, 0xffff0000, v20
	v_mul_f32_e32 v22, 0xbfb8aa3b, v33
	v_and_b32_e32 v27, 0xffff0000, v18
	v_mul_f32_e32 v18, 0xbfb8aa3b, v20
	v_exp_f32_e32 v22, v22
	v_exp_f32_e32 v23, v18
	v_pk_fma_f32 v[24:25], v[32:33], v[26:27], v[24:25] op_sel_hi:[0,1,1]
	v_pk_add_f32 v[22:23], v[22:23], 1.0 op_sel_hi:[1,0]
	s_nop 0
	v_div_scale_f32 v18, s[0:1], v23, v23, v20
	v_rcp_f32_e32 v26, v18
	s_nop 0
	v_fma_f32 v27, -v18, v26, 1.0
	v_fmac_f32_e32 v26, v27, v26
	v_div_scale_f32 v27, vcc, v20, v23, v20
	v_mul_f32_e32 v28, v27, v26
	v_fma_f32 v29, -v18, v28, v27
	v_fmac_f32_e32 v28, v29, v26
	v_fma_f32 v18, -v18, v28, v27
	v_div_fmas_f32 v18, v18, v26, v28
	v_div_fixup_f32 v23, v18, v23, v20
	v_div_scale_f32 v18, s[0:1], v22, v22, v33
	v_rcp_f32_e32 v20, v18
	s_nop 0
	v_fma_f32 v26, -v18, v20, 1.0
	v_fmac_f32_e32 v20, v26, v20
	v_div_scale_f32 v26, vcc, v33, v22, v33
	v_mul_f32_e32 v27, v26, v20
	v_fma_f32 v28, -v18, v27, v26
	v_fmac_f32_e32 v27, v28, v20
	v_fma_f32 v18, -v18, v27, v26
	v_div_fmas_f32 v18, v18, v20, v27
	v_div_fixup_f32 v22, v18, v22, v33
	v_lshlrev_b32_e32 v26, 16, v21
	v_and_b32_e32 v27, 0xffff0000, v21
	v_pk_mul_f32 v[22:23], v[24:25], v[22:23]
	v_mul_f32_e32 v18, 0xbfb8aa3b, v26
	v_lshlrev_b32_e32 v24, 16, v19
	v_and_b32_e32 v25, 0xffff0000, v19
	v_mul_f32_e32 v19, 0xbfb8aa3b, v27
	v_exp_f32_e32 v18, v18
	v_exp_f32_e32 v19, v19
	s_waitcnt lgkmcnt(2)
	v_pk_fma_f32 v[20:21], v[30:31], v[36:37], v[56:57] op_sel_hi:[1,0,1]
	v_pk_add_f32 v[18:19], v[18:19], 1.0 op_sel_hi:[1,0]
	v_pk_fma_f32 v[20:21], v[32:33], v[24:25], v[20:21] op_sel_hi:[0,1,1]
	v_div_scale_f32 v24, s[0:1], v19, v19, v27
	v_rcp_f32_e32 v25, v24
	s_nop 0
	v_fma_f32 v28, -v24, v25, 1.0
	v_fmac_f32_e32 v25, v28, v25
	v_div_scale_f32 v28, vcc, v27, v19, v27
	v_mul_f32_e32 v29, v28, v25
	v_fma_f32 v30, -v24, v29, v28
	v_fmac_f32_e32 v29, v30, v25
	v_fma_f32 v24, -v24, v29, v28
	v_div_fmas_f32 v24, v24, v25, v29
	v_div_fixup_f32 v19, v24, v19, v27
	v_div_scale_f32 v24, s[0:1], v18, v18, v26
	v_rcp_f32_e32 v25, v24
	s_nop 0
	v_fma_f32 v27, -v24, v25, 1.0
	v_fmac_f32_e32 v25, v27, v25
	v_div_scale_f32 v27, vcc, v26, v18, v26
	v_mul_f32_e32 v28, v27, v25
	v_fma_f32 v29, -v24, v28, v27
	v_fmac_f32_e32 v28, v29, v25
	v_fma_f32 v24, -v24, v28, v27
	v_div_fmas_f32 v24, v24, v25, v28
	v_div_fixup_f32 v18, v24, v18, v26
	v_pk_mul_f32 v[18:19], v[20:21], v[18:19]
	v_cvt_pk_bf16_f32 v20, v22, v23
	v_cvt_pk_bf16_f32 v21, v18, v19
	global_store_dwordx2 v[16:17], v[20:21], off offset:48
	global_load_dwordx2 v[18:19], v[42:43], off offset:64
	s_nop 0
	global_load_dwordx2 v[20:21], v[40:41], off offset:1344
	s_waitcnt vmcnt(1)
	v_lshlrev_b32_e32 v24, 16, v18
	s_waitcnt vmcnt(0)
	v_lshlrev_b32_e32 v26, 16, v20
	v_and_b32_e32 v20, 0xffff0000, v20
	v_mul_f32_e32 v22, 0xbfb8aa3b, v26
	v_and_b32_e32 v25, 0xffff0000, v18
	v_mul_f32_e32 v18, 0xbfb8aa3b, v20
	v_exp_f32_e32 v22, v22
	v_exp_f32_e32 v23, v18
	v_pk_fma_f32 v[0:1], v[32:33], v[24:25], v[0:1] op_sel_hi:[0,1,1]
	v_pk_add_f32 v[22:23], v[22:23], 1.0 op_sel_hi:[1,0]
	s_nop 0
	v_div_scale_f32 v18, s[0:1], v23, v23, v20
	v_rcp_f32_e32 v24, v18
	s_nop 0
	v_fma_f32 v25, -v18, v24, 1.0
	v_fmac_f32_e32 v24, v25, v24
	v_div_scale_f32 v25, vcc, v20, v23, v20
	v_mul_f32_e32 v27, v25, v24
	v_fma_f32 v28, -v18, v27, v25
	v_fmac_f32_e32 v27, v28, v24
	v_fma_f32 v18, -v18, v27, v25
	v_div_fmas_f32 v18, v18, v24, v27
	v_div_fixup_f32 v23, v18, v23, v20
	v_div_scale_f32 v18, s[0:1], v22, v22, v26
	v_rcp_f32_e32 v20, v18
	s_nop 0
	v_fma_f32 v24, -v18, v20, 1.0
	v_fmac_f32_e32 v20, v24, v20
	v_div_scale_f32 v24, vcc, v26, v22, v26
	v_mul_f32_e32 v25, v24, v20
	v_fma_f32 v27, -v18, v25, v24
	v_fmac_f32_e32 v25, v27, v20
	v_fma_f32 v18, -v18, v25, v24
	v_div_fmas_f32 v18, v18, v20, v25
	v_div_fixup_f32 v22, v18, v22, v26
	v_pk_mul_f32 v[0:1], v[0:1], v[22:23]
	v_lshlrev_b32_e32 v22, 16, v21
	v_and_b32_e32 v23, 0xffff0000, v21
	v_mul_f32_e32 v18, 0xbfb8aa3b, v22
	v_lshlrev_b32_e32 v20, 16, v19
	v_and_b32_e32 v21, 0xffff0000, v19
	v_mul_f32_e32 v19, 0xbfb8aa3b, v23
	v_exp_f32_e32 v18, v18
	v_exp_f32_e32 v19, v19
	v_pk_fma_f32 v[2:3], v[32:33], v[20:21], v[2:3] op_sel_hi:[0,1,1]
	v_cvt_pk_bf16_f32 v0, v0, v1
	v_pk_add_f32 v[18:19], v[18:19], 1.0 op_sel_hi:[1,0]
	s_nop 0
	v_div_scale_f32 v20, s[0:1], v19, v19, v23
	v_rcp_f32_e32 v21, v20
	s_nop 0
	v_fma_f32 v24, -v20, v21, 1.0
	v_fmac_f32_e32 v21, v24, v21
	v_div_scale_f32 v24, vcc, v23, v19, v23
	v_mul_f32_e32 v25, v24, v21
	v_fma_f32 v26, -v20, v25, v24
	v_fmac_f32_e32 v25, v26, v21
	v_fma_f32 v20, -v20, v25, v24
	v_div_fmas_f32 v20, v20, v21, v25
	v_div_fixup_f32 v19, v20, v19, v23
	v_div_scale_f32 v20, s[0:1], v18, v18, v22
	v_rcp_f32_e32 v21, v20
	s_nop 0
	v_fma_f32 v23, -v20, v21, 1.0
	v_fmac_f32_e32 v21, v23, v21
	v_div_scale_f32 v23, vcc, v22, v18, v22
	v_mul_f32_e32 v24, v23, v21
	v_fma_f32 v25, -v20, v24, v23
	v_fmac_f32_e32 v24, v25, v21
	v_fma_f32 v20, -v20, v24, v23
	v_div_fmas_f32 v20, v20, v21, v24
	v_div_fixup_f32 v18, v20, v18, v22
	v_pk_mul_f32 v[2:3], v[2:3], v[18:19]
	s_nop 0
	v_cvt_pk_bf16_f32 v1, v2, v3
	global_store_dwordx2 v[16:17], v[0:1], off offset:64
	global_load_dwordx2 v[0:1], v[42:43], off offset:80
	s_nop 0
	global_load_dwordx2 v[2:3], v[40:41], off offset:1360
	s_waitcnt vmcnt(1)
; DI float lo16(unsigned w) { return __uint_as_float(w << 16); }
; DI float hi16(unsigned w) { return __uint_as_float(w & 0xffff0000u); }
; DI float siluf_(float x) { return x / (1.f + __expf(-x)); }
; DI void nsa_item(const Params& p, int it, char* lds) {
;     ...
; #pragma unroll
;   for (int db = 0; db < 2; ++db)
; #pragma unroll
;     for (int g = 0; g < 4; ++g) {
;       const int col = h * 64 + 32 * db + 8 * g + 4 * hi;
;       const u32x2 w = *(const u32x2*)(ow + tok * 256 + col), az = *(const u32x2*)(proj + tok * NP + C_AZ + col);
;       const float v0 = (ya[db][4 * g] + o[db][4 * g] * il + g2 * lo16(w[0])) * siluf_(lo16(az[0]));
;       const float v1 = (ya[db][4 * g + 1] + o[db][4 * g + 1] * il + g2 * hi16(w[0])) * siluf_(hi16(az[0]));
;       const float v2 = (ya[db][4 * g + 2] + o[db][4 * g + 2] * il + g2 * lo16(w[1])) * siluf_(lo16(az[1]));
;       const float v3 = (ya[db][4 * g + 3] + o[db][4 * g + 3] * il + g2 * hi16(w[1])) * siluf_(hi16(az[1]));
;       u32x2 v; v[0] = pk2(v0, v1); v[1] = pk2(v2, v3);
;       *(u32x2*)(y + tok * 1024 + col) = v;
	v_lshlrev_b32_e32 v20, 16, v0
	s_waitcnt vmcnt(0)
	v_lshlrev_b32_e32 v22, 16, v2
	v_and_b32_e32 v2, 0xffff0000, v2
	v_mul_f32_e32 v18, 0xbfb8aa3b, v22
	v_and_b32_e32 v21, 0xffff0000, v0
	v_mul_f32_e32 v0, 0xbfb8aa3b, v2
	v_exp_f32_e32 v18, v18
	v_exp_f32_e32 v19, v0
	v_pk_fma_f32 v[4:5], v[32:33], v[20:21], v[4:5] op_sel_hi:[0,1,1]
	v_pk_add_f32 v[18:19], v[18:19], 1.0 op_sel_hi:[1,0]
	s_nop 0
	v_div_scale_f32 v0, s[0:1], v19, v19, v2
	v_rcp_f32_e32 v20, v0
	s_nop 0
	v_fma_f32 v21, -v0, v20, 1.0
	v_fmac_f32_e32 v20, v21, v20
	v_div_scale_f32 v21, vcc, v2, v19, v2
	v_mul_f32_e32 v23, v21, v20
	v_fma_f32 v24, -v0, v23, v21
	v_fmac_f32_e32 v23, v24, v20
	v_fma_f32 v0, -v0, v23, v21
	v_div_fmas_f32 v0, v0, v20, v23
	v_div_fixup_f32 v19, v0, v19, v2
	v_div_scale_f32 v0, s[0:1], v18, v18, v22
	v_rcp_f32_e32 v2, v0
	s_nop 0
	v_fma_f32 v20, -v0, v2, 1.0
	v_fmac_f32_e32 v2, v20, v2
	v_div_scale_f32 v20, vcc, v22, v18, v22
	v_mul_f32_e32 v21, v20, v2
	v_fma_f32 v23, -v0, v21, v20
	v_fmac_f32_e32 v21, v23, v2
	v_fma_f32 v0, -v0, v21, v20
	v_div_fmas_f32 v0, v0, v2, v21
	v_div_fixup_f32 v18, v0, v18, v22
	v_pk_mul_f32 v[4:5], v[4:5], v[18:19]
	v_lshlrev_b32_e32 v18, 16, v3
	v_and_b32_e32 v19, 0xffff0000, v3
	v_mul_f32_e32 v0, 0xbfb8aa3b, v18
	v_pk_fma_f32 v[2:3], v[6:7], v[36:37], v[48:49] op_sel_hi:[1,0,1]
	v_lshlrev_b32_e32 v6, 16, v1
	v_and_b32_e32 v7, 0xffff0000, v1
	v_mul_f32_e32 v1, 0xbfb8aa3b, v19
	v_exp_f32_e32 v0, v0
	v_exp_f32_e32 v1, v1
	v_pk_fma_f32 v[2:3], v[32:33], v[6:7], v[2:3] op_sel_hi:[0,1,1]
	v_pk_add_f32 v[0:1], v[0:1], 1.0 op_sel_hi:[1,0]
	s_nop 0
	v_div_scale_f32 v6, s[0:1], v1, v1, v19
	v_rcp_f32_e32 v7, v6
	s_nop 0
	v_fma_f32 v20, -v6, v7, 1.0
	v_fmac_f32_e32 v7, v20, v7
	v_div_scale_f32 v20, vcc, v19, v1, v19
	v_mul_f32_e32 v21, v20, v7
	v_fma_f32 v22, -v6, v21, v20
	v_fmac_f32_e32 v21, v22, v7
	v_fma_f32 v6, -v6, v21, v20
	v_div_fmas_f32 v6, v6, v7, v21
	v_div_fixup_f32 v1, v6, v1, v19
	v_div_scale_f32 v6, s[0:1], v0, v0, v18
	v_rcp_f32_e32 v7, v6
	s_nop 0
	v_fma_f32 v19, -v6, v7, 1.0
	v_fmac_f32_e32 v7, v19, v7
	v_div_scale_f32 v19, vcc, v18, v0, v18
	v_mul_f32_e32 v20, v19, v7
	v_fma_f32 v21, -v6, v20, v19
	v_fmac_f32_e32 v20, v21, v7
	v_fma_f32 v6, -v6, v20, v19
	v_div_fmas_f32 v6, v6, v7, v20
	v_div_fixup_f32 v0, v6, v0, v18
	v_pk_mul_f32 v[0:1], v[2:3], v[0:1]
	v_cvt_pk_bf16_f32 v2, v4, v5
	v_cvt_pk_bf16_f32 v3, v0, v1
	global_store_dwordx2 v[16:17], v[2:3], off offset:80
	global_load_dwordx2 v[0:1], v[42:43], off offset:96
	s_nop 0
	global_load_dwordx2 v[2:3], v[40:41], off offset:1376
	v_pk_fma_f32 v[6:7], v[8:9], v[36:37], v[46:47] op_sel_hi:[1,0,1]
	s_waitcnt vmcnt(1)
	v_lshlrev_b32_e32 v8, 16, v0
	s_waitcnt vmcnt(0)
	v_lshlrev_b32_e32 v18, 16, v2
	v_and_b32_e32 v2, 0xffff0000, v2
	v_mul_f32_e32 v4, 0xbfb8aa3b, v18
	v_and_b32_e32 v9, 0xffff0000, v0
	v_mul_f32_e32 v0, 0xbfb8aa3b, v2
	v_exp_f32_e32 v4, v4
	v_exp_f32_e32 v5, v0
	v_pk_fma_f32 v[6:7], v[32:33], v[8:9], v[6:7] op_sel_hi:[0,1,1]
	v_pk_add_f32 v[4:5], v[4:5], 1.0 op_sel_hi:[1,0]
	s_nop 0
	v_div_scale_f32 v0, s[0:1], v5, v5, v2
	v_rcp_f32_e32 v8, v0
	s_nop 0
	v_fma_f32 v9, -v0, v8, 1.0
	v_fmac_f32_e32 v8, v9, v8
	v_div_scale_f32 v9, vcc, v2, v5, v2
	v_mul_f32_e32 v19, v9, v8
	v_fma_f32 v20, -v0, v19, v9
	v_fmac_f32_e32 v19, v20, v8
	v_fma_f32 v0, -v0, v19, v9
	v_div_fmas_f32 v0, v0, v8, v19
	v_div_fixup_f32 v5, v0, v5, v2
	v_div_scale_f32 v0, s[0:1], v4, v4, v18
	v_rcp_f32_e32 v2, v0
	s_nop 0
	v_fma_f32 v8, -v0, v2, 1.0
	v_fmac_f32_e32 v2, v8, v2
	v_div_scale_f32 v8, vcc, v18, v4, v18
	v_mul_f32_e32 v9, v8, v2
	v_fma_f32 v19, -v0, v9, v8
	v_fmac_f32_e32 v9, v19, v2
	v_fma_f32 v0, -v0, v9, v8
	v_div_fmas_f32 v0, v0, v2, v9
	v_div_fixup_f32 v4, v0, v4, v18
	v_lshlrev_b32_e32 v8, 16, v3
	v_and_b32_e32 v9, 0xffff0000, v3
	v_pk_mul_f32 v[4:5], v[6:7], v[4:5]
	v_mul_f32_e32 v0, 0xbfb8aa3b, v8
	v_lshlrev_b32_e32 v6, 16, v1
	v_and_b32_e32 v7, 0xffff0000, v1
	v_mul_f32_e32 v1, 0xbfb8aa3b, v9
	v_exp_f32_e32 v0, v0
	v_exp_f32_e32 v1, v1
	v_pk_fma_f32 v[2:3], v[10:11], v[36:37], v[44:45] op_sel_hi:[1,0,1]
	v_pk_add_f32 v[0:1], v[0:1], 1.0 op_sel_hi:[1,0]
	v_pk_fma_f32 v[2:3], v[32:33], v[6:7], v[2:3] op_sel_hi:[0,1,1]
	v_div_scale_f32 v6, s[0:1], v1, v1, v9
	v_rcp_f32_e32 v7, v6
	s_nop 0
	v_fma_f32 v10, -v6, v7, 1.0
	v_fmac_f32_e32 v7, v10, v7
	v_div_scale_f32 v10, vcc, v9, v1, v9
	v_mul_f32_e32 v11, v10, v7
	v_fma_f32 v18, -v6, v11, v10
	v_fmac_f32_e32 v11, v18, v7
	v_fma_f32 v6, -v6, v11, v10
	v_div_fmas_f32 v6, v6, v7, v11
	v_div_fixup_f32 v1, v6, v1, v9
	v_div_scale_f32 v6, s[0:1], v0, v0, v8
	v_rcp_f32_e32 v7, v6
	s_nop 0
	v_fma_f32 v9, -v6, v7, 1.0
	v_fmac_f32_e32 v7, v9, v7
	v_div_scale_f32 v9, vcc, v8, v0, v8
	v_mul_f32_e32 v10, v9, v7
	v_fma_f32 v11, -v6, v10, v9
	v_fmac_f32_e32 v10, v11, v7
	v_fma_f32 v6, -v6, v10, v9
	v_div_fmas_f32 v6, v6, v7, v10
	v_div_fixup_f32 v0, v6, v0, v8
	v_pk_mul_f32 v[0:1], v[2:3], v[0:1]
	v_cvt_pk_bf16_f32 v2, v4, v5
	v_cvt_pk_bf16_f32 v3, v0, v1
	global_store_dwordx2 v[16:17], v[2:3], off offset:96
	global_load_dwordx2 v[0:1], v[42:43], off offset:112
	s_nop 0
	global_load_dwordx2 v[2:3], v[40:41], off offset:1392
	v_pk_fma_f32 v[6:7], v[12:13], v[36:37], v[38:39] op_sel_hi:[1,0,1]
	s_waitcnt vmcnt(1)
; DI float lo16(unsigned w) { return __uint_as_float(w << 16); }
; DI float hi16(unsigned w) { return __uint_as_float(w & 0xffff0000u); }
; DI float siluf_(float x) { return x / (1.f + __expf(-x)); }
; DI void nsa_item(const Params& p, int it, char* lds) {
;     ...
;     for (int g = 0; g < 4; ++g) {
;       const int col = h * 64 + 32 * db + 8 * g + 4 * hi;
;       const u32x2 w = *(const u32x2*)(ow + tok * 256 + col), az = *(const u32x2*)(proj + tok * NP + C_AZ + col);
;       const float v0 = (ya[db][4 * g] + o[db][4 * g] * il + g2 * lo16(w[0])) * siluf_(lo16(az[0]));
;       const float v1 = (ya[db][4 * g + 1] + o[db][4 * g + 1] * il + g2 * hi16(w[0])) * siluf_(hi16(az[0]));
;       const float v2 = (ya[db][4 * g + 2] + o[db][4 * g + 2] * il + g2 * lo16(w[1])) * siluf_(lo16(az[1]));
;       const float v3 = (ya[db][4 * g + 3] + o[db][4 * g + 3] * il + g2 * hi16(w[1])) * siluf_(hi16(az[1]));
;       u32x2 v; v[0] = pk2(v0, v1); v[1] = pk2(v2, v3);
;       *(u32x2*)(y + tok * 1024 + col) = v;
; __global__ void __launch_bounds__(256, 2) hybrid_megakernel(Params p) {
;     ...
;       const int gi = vb >> 4;
;       int start = 0, mine = 0;
;       for (int g2 = 0; g2 <= gi; ++g2) {
;         const int n = 32 - g2;
;         const int d = (n <= 10) ? 2 : (n <= 22) ? 1 : 0;
;         if (g2 < gi) start += 2 * d; else mine = d;
;       }
;       start += ((vb >> 3) & 1) * mine;
;       const int x = vb & 7;
;       for (int k = 0; k < mine; ++k) { const int slot = start + k; sgu_item(p, l, slot * 8 + x, lds); pool_item(p, l, slot * 8 + x, lds); dilcomb_item(p, x * 64 + slot); }
	v_lshlrev_b32_e32 v8, 16, v0
	s_waitcnt vmcnt(0)
	v_lshlrev_b32_e32 v10, 16, v2
	v_and_b32_e32 v2, 0xffff0000, v2
	v_mul_f32_e32 v4, 0xbfb8aa3b, v10
	v_and_b32_e32 v9, 0xffff0000, v0
	v_mul_f32_e32 v0, 0xbfb8aa3b, v2
	v_exp_f32_e32 v4, v4
	v_exp_f32_e32 v5, v0
	v_pk_fma_f32 v[6:7], v[32:33], v[8:9], v[6:7] op_sel_hi:[0,1,1]
	v_pk_add_f32 v[4:5], v[4:5], 1.0 op_sel_hi:[1,0]
	s_nop 0
	v_div_scale_f32 v0, s[0:1], v5, v5, v2
	v_rcp_f32_e32 v8, v0
	s_nop 0
	v_fma_f32 v9, -v0, v8, 1.0
	v_fmac_f32_e32 v8, v9, v8
	v_div_scale_f32 v9, vcc, v2, v5, v2
	v_mul_f32_e32 v11, v9, v8
	v_fma_f32 v12, -v0, v11, v9
	v_fmac_f32_e32 v11, v12, v8
	v_fma_f32 v0, -v0, v11, v9
	v_div_fmas_f32 v0, v0, v8, v11
	v_div_fixup_f32 v5, v0, v5, v2
	v_div_scale_f32 v0, s[0:1], v4, v4, v10
	v_rcp_f32_e32 v2, v0
	s_nop 0
	v_fma_f32 v8, -v0, v2, 1.0
	v_fmac_f32_e32 v2, v8, v2
	v_div_scale_f32 v8, vcc, v10, v4, v10
	v_mul_f32_e32 v9, v8, v2
	v_fma_f32 v11, -v0, v9, v8
	v_fmac_f32_e32 v9, v11, v2
	v_fma_f32 v0, -v0, v9, v8
	v_div_fmas_f32 v0, v0, v2, v9
	v_div_fixup_f32 v4, v0, v4, v10
	v_lshlrev_b32_e32 v8, 16, v3
	v_and_b32_e32 v9, 0xffff0000, v3
	v_pk_mul_f32 v[4:5], v[6:7], v[4:5]
	v_mul_f32_e32 v0, 0xbfb8aa3b, v8
	v_lshlrev_b32_e32 v6, 16, v1
	v_and_b32_e32 v7, 0xffff0000, v1
	v_mul_f32_e32 v1, 0xbfb8aa3b, v9
	v_exp_f32_e32 v0, v0
	v_exp_f32_e32 v1, v1
	s_waitcnt lgkmcnt(0)
	v_pk_fma_f32 v[2:3], v[14:15], v[36:37], v[34:35] op_sel_hi:[1,0,1]
	v_pk_add_f32 v[0:1], v[0:1], 1.0 op_sel_hi:[1,0]
	v_pk_fma_f32 v[2:3], v[32:33], v[6:7], v[2:3] op_sel_hi:[0,1,1]
	v_div_scale_f32 v6, s[0:1], v1, v1, v9
	v_rcp_f32_e32 v7, v6
	s_nop 0
	v_fma_f32 v10, -v6, v7, 1.0
	v_fmac_f32_e32 v7, v10, v7
	v_div_scale_f32 v10, vcc, v9, v1, v9
	v_mul_f32_e32 v11, v10, v7
	v_fma_f32 v12, -v6, v11, v10
	v_fmac_f32_e32 v11, v12, v7
	v_fma_f32 v6, -v6, v11, v10
	v_div_fmas_f32 v6, v6, v7, v11
	v_div_fixup_f32 v1, v6, v1, v9
	v_div_scale_f32 v6, s[0:1], v0, v0, v8
	v_rcp_f32_e32 v7, v6
	s_ashr_i32 s0, s13, 4
	s_cmp_lt_i32 s0, 0
	v_fma_f32 v9, -v6, v7, 1.0
	v_fmac_f32_e32 v7, v9, v7
	v_div_scale_f32 v9, vcc, v8, v0, v8
	v_mul_f32_e32 v10, v9, v7
	v_fma_f32 v11, -v6, v10, v9
	v_fmac_f32_e32 v10, v11, v7
	v_fma_f32 v6, -v6, v10, v9
	v_div_fmas_f32 v6, v6, v7, v10
	v_div_fixup_f32 v0, v6, v0, v8
	v_pk_mul_f32 v[0:1], v[2:3], v[0:1]
	v_cvt_pk_bf16_f32 v2, v4, v5
	v_cvt_pk_bf16_f32 v3, v0, v1
	global_store_dwordx2 v[16:17], v[2:3], off offset:112
	s_cmp_ge_u32 s0, 2
	s_cselect_b32 s1, 1, 0
	s_cmp_ge_u32 s0, 30
	s_cselect_b32 s2, 1, 0
	s_add_u32 s1, s1, s2
	s_sub_i32 s2, s0, 2
	s_max_i32 s2, s2, 0
	s_sub_i32 s4, s0, 30
	s_max_i32 s4, s4, 0
	s_add_i32 s2, s2, s4
	s_lshl_b32 s2, s2, 1
	v_mov_b32_e32 v116, s1
	v_mov_b32_e32 v0, s2
	s_cmp_eq_u32 s1, 0
	s_cbranch_scc1 .LBB0_345
